# conv phase: each workgroup takes the 12 consecutive channel-block items of one 64-token tile (DRAM/L2 locality) instead of a grid-strided order
# speedup vs baseline: 1.0185x; 1.0041x over previous
; DI void conv_phase(PPtr p, int j, ldsp lds, int tid) {
;     ...
;     const int tok = tid >> 3, cgp = tid & 7;
;     for (int item = blockIdx.x; item < 256 * 12; item += gridDim.x) {
;         const int tt = item / 12, cb = item % 12;
;         const int t0 = tt * 64, b = t0 >> 12, s0 = t0 & 4095;
.LBB0_510:
	v_readlane_b32 s0, v254, 13
	v_readlane_b32 s1, v254, 14
	s_andn2_b64 vcc, exec, s[0:1]
	s_cbranch_vccnz .LBB0_561
	v_readlane_b32 s0, v254, 51
	s_waitcnt lgkmcnt(0)
	s_add_u32 s2, s4, s0
	v_readlane_b32 s0, v254, 50
	s_addc_u32 s3, s5, s0
	v_readlane_b32 s0, v254, 53
	v_and_b32_e32 v2, 7, v42
	s_add_u32 s12, s6, s0
	v_readlane_b32 s0, v254, 52
	v_lshlrev_b32_e32 v72, 3, v2
	v_add_u32_e32 v7, 0x200, v42
	v_add_u32_e32 v8, 0x400, v42
	v_add_u32_e32 v9, 0x600, v42
	v_ashrrev_i32_e32 v70, 3, v42
	s_addc_u32 s13, s7, s0
	v_lshlrev_b32_e32 v0, 4, v2
	v_or_b32_e32 v5, 64, v72
	s_movk_i32 s0, 0x8c
	v_ashrrev_i32_e32 v74, 3, v7
	v_ashrrev_i32_e32 v76, 3, v8
	v_ashrrev_i32_e32 v78, 3, v9
	v_lshl_add_u32 v3, v70, 1, 0
	v_add_u32_e32 v4, 0, v0
	v_mul_u32_u24_e32 v2, 0x460, v2
	v_mul_u32_u24_e32 v5, 0x8c, v5
	v_mul_lo_u32 v6, v70, s0
	v_mul_lo_u32 v7, v74, s0
	v_mul_lo_u32 v8, v76, s0
	v_mul_lo_u32 v9, v78, s0
	v_mov_b32_e32 v73, v1
	v_ashrrev_i32_e32 v71, 31, v70
	v_ashrrev_i32_e32 v75, 31, v74
	v_ashrrev_i32_e32 v77, 31, v76
	v_ashrrev_i32_e32 v79, 31, v78
	v_lshl_add_u64 v[80:81], s[10:11], 0, v[0:1]
	s_lshl_b32 s18, s90, 8
	v_add_u32_e32 v84, v4, v6
	v_add_u32_e32 v85, v4, v7
	v_add_u32_e32 v86, v4, v8
	v_add_u32_e32 v87, v4, v9
	v_add_u32_e32 v88, v3, v2
	v_add_u32_e32 v89, v3, v5
	v_readlane_b32 s19, v254, 24
	s_mov_b32 s20, s64
	s_cmpk_lg_u32 s90, 0x100
	s_cbranch_scc1 .LBB0_513
	s_mul_i32 s20, s64, 12
	s_lshl_b32 s19, s20, 8
	s_branch .LBB0_513
.LBB0_512:
	s_cmpk_lg_u32 s90, 0x100
	s_cbranch_scc1 .Lconv_std_latch
	s_add_i32 s20, s20, 1
	s_addk_i32 s19, 0x100
	s_mul_i32 s0, s64, 12
	s_sub_i32 s0, s20, s0
	s_cmp_lt_u32 s0, 12
	s_cbranch_scc1 .LBB0_513
	s_branch .LBB0_561
